# v18 without the wait for the completion-counter atomics on the producer side (fire and forget)
# baseline (speedup 1.0000x reference)
; #define GASP __attribute__((address_space(1)))
; __device__ __forceinline__ unsigned xb_add(unsigned* p, unsigned v) { return __hip_atomic_fetch_add(p, v, __ATOMIC_RELAXED, __HIP_MEMORY_SCOPE_AGENT); }
; template <int MODE> ...
;     ...
;         if (STn) { s = wave_sum(s); q = wave_sum(q);
;             if (lane < 16) *(GASP f32x2*)(STn + (size_t)row * 32 + 2 * lane) = lane == 0 ? (f32x2){s, q} : (f32x2){0.f, 0.f}; }
; __device__ __forceinline__ void xcd_barrier(const XcdBarrier& b) {
;     ...
;         const unsigned old = xb_add(&bar[XB_XSUB(b.x)], 1u);
;         const unsigned gen = old / nloc;
;         if (old + 1u == (gen + 1u) * nloc) {
;             __builtin_amdgcn_fence(__ATOMIC_RELEASE, "agent");
;             asm volatile("s_waitcnt vmcnt(0)" ::: "memory");
;             const unsigned og = xb_add(&bar[XB_TOP], 1u);
.LBB0_359:
	s_or_b64 exec, exec, s[6:7]
	s_waitcnt vmcnt(0) lgkmcnt(0)
	s_barrier
	s_cmpk_gt_u32 s2, 0x7f
	s_cbranch_scc1 .Lq3_prod_done
	s_mov_b64 s[38:39], exec
	v_readlane_b32 s0, v252, 6
	v_readlane_b32 s1, v252, 7
	s_and_b64 s[0:1], s[38:39], s[0:1]
	s_mov_b64 exec, s[0:1]
	s_cbranch_execz .Lq3_prod_restore
	buffer_wbl2 sc1
	s_waitcnt vmcnt(0)
	s_add_u32 s98, s52, 0x2fb46880
	s_addc_u32 s99, s53, 0
	v_mov_b32_e32 v0, 0
	v_mov_b32_e32 v1, 1
	global_atomic_add v0, v1, s[98:99]
.Lq3_prod_restore:
	s_mov_b64 exec, s[38:39]

; #define GASP __attribute__((address_space(1)))
; __device__ __forceinline__ unsigned xb_add(unsigned* p, unsigned v) { return __hip_atomic_fetch_add(p, v, __ATOMIC_RELAXED, __HIP_MEMORY_SCOPE_AGENT); }
; template <int MODE> ...
;     ...
;         if (STn) { s = wave_sum(s); q = wave_sum(q);
;             if (lane < 16) *(GASP f32x2*)(STn + (size_t)row * 32 + 2 * lane) = lane == 0 ? (f32x2){s, q} : (f32x2){0.f, 0.f}; }
; __device__ __forceinline__ void xcd_barrier(const XcdBarrier& b) {
;     ...
;         const unsigned old = xb_add(&bar[XB_XSUB(b.x)], 1u);
;         const unsigned gen = old / nloc;
;         if (old + 1u == (gen + 1u) * nloc) {
;             __builtin_amdgcn_fence(__ATOMIC_RELEASE, "agent");
;             asm volatile("s_waitcnt vmcnt(0)" ::: "memory");
;             const unsigned og = xb_add(&bar[XB_TOP], 1u);
.LBB0_1132:
	s_or_b64 exec, exec, s[12:13]
	v_readlane_b32 s0, v252, 12
	v_readlane_b32 s1, v252, 13
	s_andn2_b64 vcc, exec, s[0:1]
	s_cbranch_vccnz .LBB0_1178
	s_waitcnt vmcnt(0) lgkmcnt(0)
	s_barrier
	s_cmpk_gt_u32 s2, 0x7f
	s_cbranch_scc1 .Lq7_prod_done
	s_mov_b64 s[38:39], exec
	v_readlane_b32 s0, v252, 6
	v_readlane_b32 s1, v252, 7
	s_and_b64 s[0:1], s[38:39], s[0:1]
	s_mov_b64 exec, s[0:1]
	s_cbranch_execz .Lq7_prod_restore
	buffer_wbl2 sc1
	s_waitcnt vmcnt(0)
	s_add_u32 s98, s52, 0x2fb46840
	s_addc_u32 s99, s53, 0
	v_mov_b32_e32 v0, 0
	v_mov_b32_e32 v1, 1
	global_atomic_add v0, v1, s[98:99]
.Lq7_prod_restore:
	s_mov_b64 exec, s[38:39]

; #define GASP __attribute__((address_space(1)))
; __device__ __forceinline__ unsigned xb_add(unsigned* p, unsigned v) { return __hip_atomic_fetch_add(p, v, __ATOMIC_RELAXED, __HIP_MEMORY_SCOPE_AGENT); }
; template <int MODE> ...
;     ...
;         for (int j = 0; j < 4; ++j) { const f32x4 y = ((acc[j] - ((const GASP f32x4*)c1)[64 * j + lane] * mu) * rstd + ((const GASP f32x4*)c2)[64 * j + lane]) * scale;
;             u32x2 w; w.x = pk2(y[0], y[1]); w.y = pk2(y[2], y[3]); ((GASP u32x2*)(ob + (size_t)row * D))[64 * j + lane] = w; }
; __device__ __forceinline__ void xcd_barrier(const XcdBarrier& b) {
;     ...
;         const unsigned old = xb_add(&bar[XB_XSUB(b.x)], 1u);
;         const unsigned gen = old / nloc;
;         if (old + 1u == (gen + 1u) * nloc) {
;             __builtin_amdgcn_fence(__ATOMIC_RELEASE, "agent");
;             asm volatile("s_waitcnt vmcnt(0)" ::: "memory");
;             const unsigned og = xb_add(&bar[XB_TOP], 1u);
.LBB0_1274:
	s_or_b64 exec, exec, s[8:9]
	v_readlane_b32 s0, v252, 12
	v_readlane_b32 s1, v252, 13
	s_andn2_b64 vcc, exec, s[0:1]
	s_cbranch_vccnz .LBB0_1320
	s_waitcnt vmcnt(0) lgkmcnt(0)
	s_barrier
	s_cmpk_gt_u32 s2, 0x7f
	s_cbranch_scc1 .Lq15_prod_done
	s_mov_b64 s[38:39], exec
	v_readlane_b32 s0, v252, 6
	v_readlane_b32 s1, v252, 7
	s_and_b64 s[0:1], s[38:39], s[0:1]
	s_mov_b64 exec, s[0:1]
	s_cbranch_execz .Lq15_prod_restore
	buffer_wbl2 sc1
	s_waitcnt vmcnt(0)
	s_add_u32 s98, s52, 0x2fb46800
	s_addc_u32 s99, s53, 0
	v_mov_b32_e32 v0, 0
	v_mov_b32_e32 v1, 1
	global_atomic_add v0, v1, s[98:99]
.Lq15_prod_restore:
	s_mov_b64 exec, s[38:39]

; #define GASP __attribute__((address_space(1)))
; __device__ __forceinline__ unsigned xb_add(unsigned* p, unsigned v) { return __hip_atomic_fetch_add(p, v, __ATOMIC_RELAXED, __HIP_MEMORY_SCOPE_AGENT); }
; template <int MODE> ...
;     ...
;         if (STn) { s = wave_sum(s); q = wave_sum(q);
;             if (lane < 16) *(GASP f32x2*)(STn + (size_t)row * 32 + 2 * lane) = lane == 0 ? (f32x2){s, q} : (f32x2){0.f, 0.f}; }
; __device__ __forceinline__ void xcd_barrier(const XcdBarrier& b) {
;     ...
;         const unsigned old = xb_add(&bar[XB_XSUB(b.x)], 1u);
;         const unsigned gen = old / nloc;
;         if (old + 1u == (gen + 1u) * nloc) {
;             __builtin_amdgcn_fence(__ATOMIC_RELEASE, "agent");
;             asm volatile("s_waitcnt vmcnt(0)" ::: "memory");
;             const unsigned og = xb_add(&bar[XB_TOP], 1u);
.LBB0_1512:
	s_or_b64 exec, exec, s[12:13]
	s_waitcnt vmcnt(0) lgkmcnt(0)
	s_barrier
	s_cmpk_gt_u32 s2, 0x7f
	s_cbranch_scc1 .Lq11_prod_done
	s_mov_b64 s[38:39], exec
	v_readlane_b32 s0, v252, 6
	v_readlane_b32 s1, v252, 7
	s_and_b64 s[0:1], s[38:39], s[0:1]
	s_mov_b64 exec, s[0:1]
	s_cbranch_execz .Lq11_prod_restore
	buffer_wbl2 sc1
	s_waitcnt vmcnt(0)
	s_add_u32 s98, s52, 0x2fb468c0
	s_addc_u32 s99, s53, 0
	v_mov_b32_e32 v0, 0
	v_mov_b32_e32 v1, 1
	global_atomic_add v0, v1, s[98:99]
.Lq11_prod_restore:
	s_mov_b64 exec, s[38:39]
